# P5: HGRN next-chunk loads interleaved into the VALU-heavy part A via SGPR-base addressing; LRU next-chunk loads prefetched into spare VGPRs after barrier 1
# speedup vs baseline: 1.0064x; 1.0064x over previous
; __device__ __forceinline__ float bf2f(bf16_t b) { return __uint_as_float(((unsigned)b) << 16); }
; __device__ __forceinline__ void lru_item(LAS unsigned char* lds, int item, const bf16_t* XB, const bf16_t* GB, const float* conv_w, const float* conv_b, const bf16_t* WLA, const bf16_t* WLX,
;                                          const float* ba, const float* bx, const float* lam, bf16_t* YAB) {
;     ...
;         float xin[19];
;         { const int t0 = c * 64 + part * 16;
; #pragma unroll
;           for (int i = 0; i < 19; ++i) { const int t = t0 - 3 + i; xin[i] = (t >= 0) ? bf2f(XB[(row0 + t) * HW + colc]) : 0.f; } }
;         float gbv[8];
; #pragma unroll
;         for (int i = 0; i < 8; ++i) gbv[i] = bf2f(GB[(row0 + (size_t)c * 64 + g * 8 + i) * HW + colo]);
.LBB0_639:
	s_cmp_lg_u32 s61, 0
	s_cbranch_scc1 .Llru_top_b
	s_lshl_b32 s96, s61, 6
	v_add_u32_e32 v5, s96, v41
	v_cmp_lt_i32_e64 s[0:1], -1, v5
	v_cmp_lt_i32_e64 s[38:39], -2, v5
	v_max_i32_e32 v26, 0, v5
	v_add_u32_e32 v26, s60, v26
	v_lshlrev_b64 v[0:1], 11, v[26:27]
	v_add_u32_e32 v26, 1, v5
	v_lshl_add_u64 v[0:1], v[20:21], 0, v[0:1]
	v_max_i32_e32 v26, 0, v26
	global_load_ushort v231, v[0:1], off
	v_add_u32_e32 v26, s60, v26
	v_lshlrev_b64 v[0:1], 11, v[26:27]
	v_add_u32_e32 v26, 2, v5
	v_lshl_add_u64 v[0:1], v[20:21], 0, v[0:1]
	v_max_i32_e32 v26, 0, v26
	global_load_ushort v246, v[0:1], off
	v_add_u32_e32 v26, s60, v26
	v_lshlrev_b64 v[0:1], 11, v[26:27]
	v_lshl_add_u64 v[0:1], v[20:21], 0, v[0:1]
	global_load_ushort v247, v[0:1], off
	v_add_u32_e32 v26, s96, v96
	v_lshlrev_b64 v[0:1], 11, v[26:27]
	v_add_u32_e32 v26, s71, v5
	v_lshlrev_b64 v[6:7], 11, v[26:27]
	v_lshl_add_u64 v[0:1], v[20:21], 0, v[0:1]
	v_lshl_add_u64 v[6:7], v[20:21], 0, v[6:7]
	v_add_u32_e32 v26, s51, v5
	global_load_ushort v0, v[0:1], off
	s_nop 0
	global_load_ushort v1, v[6:7], off
	v_lshlrev_b64 v[6:7], 11, v[26:27]
	v_lshl_add_u64 v[6:7], v[20:21], 0, v[6:7]
	v_add_u32_e32 v26, s97, v5
	global_load_ushort v181, v[6:7], off
	v_lshlrev_b64 v[6:7], 11, v[26:27]
	v_lshl_add_u64 v[6:7], v[20:21], 0, v[6:7]
	v_add_u32_e32 v26, s84, v5
	global_load_ushort v186, v[6:7], off
	v_lshlrev_b64 v[6:7], 11, v[26:27]
	v_lshl_add_u64 v[6:7], v[20:21], 0, v[6:7]
	v_add_u32_e32 v26, s85, v5
	global_load_ushort v184, v[6:7], off
	v_lshlrev_b64 v[6:7], 11, v[26:27]
	v_lshl_add_u64 v[6:7], v[20:21], 0, v[6:7]
	v_add_u32_e32 v26, s74, v5
	global_load_ushort v185, v[6:7], off
	v_lshlrev_b64 v[6:7], 11, v[26:27]
	v_lshl_add_u64 v[6:7], v[20:21], 0, v[6:7]
	v_add_u32_e32 v26, s75, v5
	global_load_ushort v182, v[6:7], off
	v_lshlrev_b64 v[6:7], 11, v[26:27]
	v_lshl_add_u64 v[6:7], v[20:21], 0, v[6:7]
	v_add_u32_e32 v26, s76, v5
	global_load_ushort v183, v[6:7], off
	v_lshlrev_b64 v[6:7], 11, v[26:27]
	v_lshl_add_u64 v[6:7], v[20:21], 0, v[6:7]
	v_add_u32_e32 v26, s77, v5
	global_load_ushort v14, v[6:7], off
	v_lshlrev_b64 v[6:7], 11, v[26:27]
	v_lshl_add_u64 v[6:7], v[20:21], 0, v[6:7]
	v_add_u32_e32 v26, s78, v5
	global_load_ushort v15, v[6:7], off
	v_lshlrev_b64 v[6:7], 11, v[26:27]
	v_lshl_add_u64 v[6:7], v[20:21], 0, v[6:7]
	v_add_u32_e32 v26, s79, v5
	global_load_ushort v12, v[6:7], off
	v_lshlrev_b64 v[6:7], 11, v[26:27]
	v_lshl_add_u64 v[6:7], v[20:21], 0, v[6:7]
	v_add_u32_e32 v26, s82, v5
	global_load_ushort v13, v[6:7], off
	v_lshlrev_b64 v[6:7], 11, v[26:27]
	v_lshl_add_u64 v[6:7], v[20:21], 0, v[6:7]
	v_add_u32_e32 v26, s83, v5
	global_load_ushort v10, v[6:7], off
	v_lshlrev_b64 v[6:7], 11, v[26:27]
	v_lshl_add_u64 v[6:7], v[20:21], 0, v[6:7]
	v_add_u32_e32 v26, s86, v5
	global_load_ushort v11, v[6:7], off
	v_lshlrev_b64 v[6:7], 11, v[26:27]
	v_lshl_add_u64 v[6:7], v[20:21], 0, v[6:7]
	v_add_u32_e32 v26, s87, v5
	global_load_ushort v8, v[6:7], off
	v_lshlrev_b64 v[6:7], 11, v[26:27]
	v_add_u32_e32 v26, s96, v95
	v_lshl_add_u64 v[6:7], v[20:21], 0, v[6:7]
	v_lshl_or_b32 v5, v26, 11, v97
	v_or_b32_e32 v98, 1, v26
	global_load_ushort v9, v[6:7], off
	global_load_ushort v169, v5, s[68:69]
	v_lshl_or_b32 v5, v98, 11, v97
	v_or_b32_e32 v99, 2, v26
	global_load_ushort v170, v5, s[68:69]
	v_lshl_or_b32 v5, v99, 11, v97
	v_or_b32_e32 v100, 3, v26
	global_load_ushort v171, v5, s[68:69]
	v_lshl_or_b32 v5, v100, 11, v97
	v_or_b32_e32 v101, 4, v26
	global_load_ushort v172, v5, s[68:69]
	v_lshl_or_b32 v5, v101, 11, v97
	v_or_b32_e32 v102, 5, v26
	global_load_ushort v173, v5, s[68:69]
	v_lshl_or_b32 v5, v102, 11, v97
	v_or_b32_e32 v103, 6, v26
	global_load_ushort v174, v5, s[68:69]
	v_lshl_or_b32 v5, v103, 11, v97
	v_or_b32_e32 v168, 7, v26
	global_load_ushort v175, v5, s[68:69]
	v_lshl_or_b32 v5, v168, 11, v97
	global_load_ushort v180, v5, s[68:69]
	s_branch .Llru_top_done
; __device__ __forceinline__ bf16_t f2bf(float f) { return (bf16_t)(cvt_pk_bf16(f, 0.f) & 0xffffu); }
; __device__ __forceinline__ float bf2f(bf16_t b) { return __uint_as_float(((unsigned)b) << 16); }
; __device__ __forceinline__ void lru_item(LAS unsigned char* lds, int item, const bf16_t* XB, const bf16_t* GB, const float* conv_w, const float* conv_b, const bf16_t* WLA, const bf16_t* WLX,
;                                          const float* ba, const float* bx, const float* lam, bf16_t* YAB) {
;     ...
;         { const int t0 = c * 64 + part * 16;
; #pragma unroll
;           for (int i = 0; i < 19; ++i) { const int t = t0 - 3 + i; xin[i] = (t >= 0) ? bf2f(XB[(row0 + t) * HW + colc]) : 0.f; } }
;         float gbv[8];
; #pragma unroll
;         for (int i = 0; i < 8; ++i) gbv[i] = bf2f(GB[(row0 + (size_t)c * 64 + g * 8 + i) * HW + colo]);
; #pragma unroll
;         for (int i = 0; i < 16; ++i) {
;             const float xc = cb + w0 * xin[i + 3] + w1 * xin[i + 2] + w2 * xin[i + 1] + w3 * xin[i];
;             XC[(part * 16 + i) * 136 + ch] = f2bf(xc);
;             if (own) XCF[(part * 16 + i) * 65 + (ch & 63)] = xc;
;         }
.Llru_top_b:
	s_waitcnt vmcnt(8)
	s_lshl_b32 s96, s61, 6
	v_add_u32_e32 v5, s96, v41
	v_cmp_lt_i32_e64 s[0:1], -1, v5
	v_cmp_lt_i32_e64 s[38:39], -2, v5
	v_max_i32_e32 v26, 0, v5
	v_add_u32_e32 v26, s60, v26
	v_lshlrev_b64 v[0:1], 11, v[26:27]
	v_add_u32_e32 v26, 1, v5
	v_lshl_add_u64 v[0:1], v[20:21], 0, v[0:1]
	v_max_i32_e32 v26, 0, v26
	v_mov_b32_e32 v231, v194
	v_add_u32_e32 v26, s60, v26
	v_lshlrev_b64 v[0:1], 11, v[26:27]
	v_add_u32_e32 v26, 2, v5
	v_lshl_add_u64 v[0:1], v[20:21], 0, v[0:1]
	v_max_i32_e32 v26, 0, v26
	v_mov_b32_e32 v246, v195
	v_add_u32_e32 v26, s60, v26
	v_lshlrev_b64 v[0:1], 11, v[26:27]
	v_lshl_add_u64 v[0:1], v[20:21], 0, v[0:1]
	v_mov_b32_e32 v247, v196
	v_add_u32_e32 v26, s96, v96
	v_lshlrev_b64 v[0:1], 11, v[26:27]
	v_add_u32_e32 v26, s71, v5
	v_lshlrev_b64 v[6:7], 11, v[26:27]
	v_lshl_add_u64 v[0:1], v[20:21], 0, v[0:1]
	v_lshl_add_u64 v[6:7], v[20:21], 0, v[6:7]
	v_add_u32_e32 v26, s51, v5
	v_mov_b32_e32 v0, v197
	s_nop 0
	v_mov_b32_e32 v1, v198
	v_lshlrev_b64 v[6:7], 11, v[26:27]
	v_lshl_add_u64 v[6:7], v[20:21], 0, v[6:7]
	v_add_u32_e32 v26, s97, v5
	v_mov_b32_e32 v181, v199
	v_lshlrev_b64 v[6:7], 11, v[26:27]
	v_lshl_add_u64 v[6:7], v[20:21], 0, v[6:7]
	v_add_u32_e32 v26, s84, v5
	v_mov_b32_e32 v186, v200
	v_lshlrev_b64 v[6:7], 11, v[26:27]
	v_lshl_add_u64 v[6:7], v[20:21], 0, v[6:7]
	v_add_u32_e32 v26, s85, v5
	v_mov_b32_e32 v184, v201
	v_lshlrev_b64 v[6:7], 11, v[26:27]
	v_lshl_add_u64 v[6:7], v[20:21], 0, v[6:7]
	v_add_u32_e32 v26, s74, v5
	v_mov_b32_e32 v185, v202
	v_lshlrev_b64 v[6:7], 11, v[26:27]
	v_lshl_add_u64 v[6:7], v[20:21], 0, v[6:7]
	v_add_u32_e32 v26, s75, v5
	v_mov_b32_e32 v182, v203
	v_lshlrev_b64 v[6:7], 11, v[26:27]
	v_lshl_add_u64 v[6:7], v[20:21], 0, v[6:7]
	v_add_u32_e32 v26, s76, v5
	v_mov_b32_e32 v183, v204
	v_lshlrev_b64 v[6:7], 11, v[26:27]
	v_lshl_add_u64 v[6:7], v[20:21], 0, v[6:7]
	v_add_u32_e32 v26, s77, v5
	v_mov_b32_e32 v14, v205
	v_lshlrev_b64 v[6:7], 11, v[26:27]
	v_lshl_add_u64 v[6:7], v[20:21], 0, v[6:7]
	v_add_u32_e32 v26, s78, v5
	v_mov_b32_e32 v15, v206
	v_lshlrev_b64 v[6:7], 11, v[26:27]
	v_lshl_add_u64 v[6:7], v[20:21], 0, v[6:7]
	v_add_u32_e32 v26, s79, v5
	v_mov_b32_e32 v12, v207
	v_lshlrev_b64 v[6:7], 11, v[26:27]
	v_lshl_add_u64 v[6:7], v[20:21], 0, v[6:7]
	v_add_u32_e32 v26, s82, v5
	v_mov_b32_e32 v13, v208
	v_lshlrev_b64 v[6:7], 11, v[26:27]
	v_lshl_add_u64 v[6:7], v[20:21], 0, v[6:7]
	v_add_u32_e32 v26, s83, v5
	v_mov_b32_e32 v10, v209
	v_lshlrev_b64 v[6:7], 11, v[26:27]
	v_lshl_add_u64 v[6:7], v[20:21], 0, v[6:7]
	v_add_u32_e32 v26, s86, v5
	v_mov_b32_e32 v11, v210
	v_lshlrev_b64 v[6:7], 11, v[26:27]
	v_lshl_add_u64 v[6:7], v[20:21], 0, v[6:7]
	v_add_u32_e32 v26, s87, v5
	v_mov_b32_e32 v8, v211
	v_lshlrev_b64 v[6:7], 11, v[26:27]
	v_add_u32_e32 v26, s96, v95
	v_lshl_add_u64 v[6:7], v[20:21], 0, v[6:7]
	v_lshl_or_b32 v5, v26, 11, v97
	v_or_b32_e32 v98, 1, v26
	v_mov_b32_e32 v9, v212
	v_mov_b32_e32 v169, v213
	v_lshl_or_b32 v5, v98, 11, v97
	v_or_b32_e32 v99, 2, v26
	v_mov_b32_e32 v170, v214
	v_lshl_or_b32 v5, v99, 11, v97
	v_or_b32_e32 v100, 3, v26
	v_mov_b32_e32 v171, v215
	v_lshl_or_b32 v5, v100, 11, v97
	v_or_b32_e32 v101, 4, v26
	v_mov_b32_e32 v172, v216
	v_lshl_or_b32 v5, v101, 11, v97
	v_or_b32_e32 v102, 5, v26
	v_mov_b32_e32 v173, v217
	v_lshl_or_b32 v5, v102, 11, v97
	v_or_b32_e32 v103, 6, v26
	v_mov_b32_e32 v174, v218
	v_lshl_or_b32 v5, v103, 11, v97
	v_or_b32_e32 v168, 7, v26
	v_mov_b32_e32 v175, v219
	v_lshl_or_b32 v5, v168, 11, v97
	v_mov_b32_e32 v180, v220
.Llru_top_done:
	s_waitcnt vmcnt(23)
	v_lshlrev_b32_e32 v2, 16, v231
	v_lshlrev_b32_e32 v3, 16, v246
	v_lshlrev_b32_e32 v4, 16, v247
	v_cndmask_b32_e64 v2, 0, v2, s[0:1]
	v_cndmask_b32_e64 v3, 0, v3, s[38:39]
	v_cndmask_b32_e64 v4, 0, v4, s[0:1]
	v_lshlrev_b32_e32 v0, 16, v0
	v_mov_b32_e32 v5, v0
	v_pk_mul_f32 v[6:7], v[16:17], v[4:5]
	s_waitcnt vmcnt(22)
	v_lshlrev_b32_e32 v1, 16, v1
	v_add_f32_e32 v5, v81, v7
	v_add_f32_e32 v5, v6, v5
	v_pk_mul_f32 v[6:7], v[18:19], v[2:3]
	s_nop 0
	v_add_f32_e32 v2, v7, v5
	v_add_f32_e32 v2, v6, v2
	v_pk_mul_f32 v[6:7], v[16:17], v[0:1]
	v_cvt_pk_bf16_f32 v5, v2, s0
	v_add_f32_e32 v7, v81, v7
	ds_write_b16 v149, v5
	s_and_saveexec_b64 s[0:1], vcc
	s_xor_b64 s[0:1], exec, s[0:1]
	v_mov_b32_e32 v2, v3
	v_mov_b32_e32 v3, v4
	v_add_f32_e32 v5, v6, v7
	v_pk_mul_f32 v[2:3], v[18:19], v[2:3]
	s_nop 0
	v_add_f32_e32 v3, v3, v5
	v_add_f32_e32 v5, v2, v3
	s_or_saveexec_b64 s[0:1], s[0:1]
	v_add_u32_e32 v187, 0xcc00, v163
	s_xor_b64 exec, exec, s[0:1]
	s_cbranch_execz .LBB0_647
	v_add_f32_e32 v5, v6, v7
	v_mov_b32_e32 v6, v3
	v_mov_b32_e32 v7, v4
	v_pk_mul_f32 v[6:7], v[18:19], v[6:7]
	s_nop 0
	v_add_f32_e32 v3, v7, v5
	v_add_f32_e32 v5, v6, v3
	ds_write2_b32 v187, v2, v5 offset1:65

; #define LAS __attribute__((address_space(3)))
; __device__ __forceinline__ bf16_t f2bf(float f) { return (bf16_t)(cvt_pk_bf16(f, 0.f) & 0xffffu); }
; __device__ __forceinline__ float bf2f(bf16_t b) { return __uint_as_float(((unsigned)b) << 16); }
; #define MFMA16(a, b, c) __builtin_amdgcn_mfma_f32_16x16x32_bf16((a), (b), (c), 0, 0, 0)
; __device__ __forceinline__ void lru_item(LAS unsigned char* lds, int item, const bf16_t* XB, const bf16_t* GB, const float* conv_w, const float* conv_b, const bf16_t* WLA, const bf16_t* WLX,
;                                          const float* ba, const float* bx, const float* lam, bf16_t* YAB) {
;     ...
;     for (int c = 0; c < 64; ++c) {
;         float xin[19];
;         { const int t0 = c * 64 + part * 16;
; #pragma unroll
;           for (int i = 0; i < 19; ++i) { const int t = t0 - 3 + i; xin[i] = (t >= 0) ? bf2f(XB[(row0 + t) * HW + colc]) : 0.f; } }
;         float gbv[8];
; #pragma unroll
;         for (int i = 0; i < 8; ++i) gbv[i] = bf2f(GB[(row0 + (size_t)c * 64 + g * 8 + i) * HW + colo]);
; #pragma unroll
;         for (int i = 0; i < 16; ++i) {
;             const float xc = cb + w0 * xin[i + 3] + w1 * xin[i + 2] + w2 * xin[i + 1] + w3 * xin[i];
;             XC[(part * 16 + i) * 136 + ch] = f2bf(xc);
;             if (own) XCF[(part * 16 + i) * 65 + (ch & 63)] = xc;
;         }
;         __syncthreads();
;         {
;             f32x4 ar[2], ai[2];
;             ar[0] = (f32x4){0.f, 0.f, 0.f, 0.f}; ar[1] = ar[0]; ai[0] = ar[0]; ai[1] = ar[0];
; #pragma unroll
;             for (int ks = 0; ks < 4; ++ks) {
;                 const bf16x8 af = *(const LAS bf16x8*)(XC + (st * 16 + l15) * 136 + ks * 32 + quad * 8);
; #pragma unroll
;                 for (int c2 = 0; c2 < 2; ++c2) {
;                     const bf16x8 fa = *(const LAS bf16x8*)(WL + ((ct0 + c2) * 16 + l15) * 136 + ks * 32 + quad * 8);
;                     const bf16x8 fx = *(const LAS bf16x8*)(WL + (64 + (ct0 + c2) * 16 + l15) * 136 + ks * 32 + quad * 8);
;                     ar[c2] = MFMA16(af, fa, ar[c2]); ai[c2] = MFMA16(af, fx, ai[c2]);
;                 }
;             }
.LBB0_675:
	s_or_b64 exec, exec, s[0:1]
	v_cvt_pk_bf16_f32 v0, v4, s0
	ds_write_b16 v151, v0
	s_waitcnt lgkmcnt(0)
	s_barrier
	s_cmp_eq_u32 s61, 63
	s_cbranch_scc1 .Llru_nopf
	s_lshl_b32 s98, s61, 6
	s_add_i32 s98, s98, 64
	v_add_u32_e32 v230, s98, v41
	v_mov_b32_e32 v229, 0
	v_add_u32_e32 v228, s60, v230
	v_lshlrev_b64 v[226:227], 11, v[228:229]
	v_lshl_add_u64 v[226:227], v[20:21], 0, v[226:227]
	global_load_ushort v194, v[226:227], off
	v_add_u32_e32 v228, 1, v228
	v_lshlrev_b64 v[226:227], 11, v[228:229]
	v_lshl_add_u64 v[226:227], v[20:21], 0, v[226:227]
	global_load_ushort v195, v[226:227], off
	v_add_u32_e32 v228, 1, v228
	v_lshlrev_b64 v[226:227], 11, v[228:229]
	v_lshl_add_u64 v[226:227], v[20:21], 0, v[226:227]
	global_load_ushort v196, v[226:227], off
	v_add_u32_e32 v228, 1, v228
	v_lshlrev_b64 v[226:227], 11, v[228:229]
	v_lshl_add_u64 v[226:227], v[20:21], 0, v[226:227]
	global_load_ushort v197, v[226:227], off
	v_add_u32_e32 v228, 1, v228
	v_lshlrev_b64 v[226:227], 11, v[228:229]
	v_lshl_add_u64 v[226:227], v[20:21], 0, v[226:227]
	global_load_ushort v198, v[226:227], off
	v_add_u32_e32 v228, 1, v228
	v_lshlrev_b64 v[226:227], 11, v[228:229]
	v_lshl_add_u64 v[226:227], v[20:21], 0, v[226:227]
	global_load_ushort v199, v[226:227], off
	v_add_u32_e32 v228, 1, v228
	v_lshlrev_b64 v[226:227], 11, v[228:229]
	v_lshl_add_u64 v[226:227], v[20:21], 0, v[226:227]
	global_load_ushort v200, v[226:227], off
	v_add_u32_e32 v228, 1, v228
	v_lshlrev_b64 v[226:227], 11, v[228:229]
	v_lshl_add_u64 v[226:227], v[20:21], 0, v[226:227]
	global_load_ushort v201, v[226:227], off
	v_add_u32_e32 v228, 1, v228
	v_lshlrev_b64 v[226:227], 11, v[228:229]
	v_lshl_add_u64 v[226:227], v[20:21], 0, v[226:227]
	global_load_ushort v202, v[226:227], off
	v_add_u32_e32 v228, 1, v228
	v_lshlrev_b64 v[226:227], 11, v[228:229]
	v_lshl_add_u64 v[226:227], v[20:21], 0, v[226:227]
	global_load_ushort v203, v[226:227], off
	v_add_u32_e32 v228, 1, v228
	v_lshlrev_b64 v[226:227], 11, v[228:229]
	v_lshl_add_u64 v[226:227], v[20:21], 0, v[226:227]
	global_load_ushort v204, v[226:227], off
	v_add_u32_e32 v228, 1, v228
	v_lshlrev_b64 v[226:227], 11, v[228:229]
	v_lshl_add_u64 v[226:227], v[20:21], 0, v[226:227]
	global_load_ushort v205, v[226:227], off
	v_add_u32_e32 v228, 1, v228
	v_lshlrev_b64 v[226:227], 11, v[228:229]
	v_lshl_add_u64 v[226:227], v[20:21], 0, v[226:227]
	global_load_ushort v206, v[226:227], off
	v_add_u32_e32 v228, 1, v228
	v_lshlrev_b64 v[226:227], 11, v[228:229]
	v_lshl_add_u64 v[226:227], v[20:21], 0, v[226:227]
	global_load_ushort v207, v[226:227], off
	v_add_u32_e32 v228, 1, v228
	v_lshlrev_b64 v[226:227], 11, v[228:229]
	v_lshl_add_u64 v[226:227], v[20:21], 0, v[226:227]
	global_load_ushort v208, v[226:227], off
	v_add_u32_e32 v228, 1, v228
	v_lshlrev_b64 v[226:227], 11, v[228:229]
	v_lshl_add_u64 v[226:227], v[20:21], 0, v[226:227]
	global_load_ushort v209, v[226:227], off
	v_add_u32_e32 v228, 1, v228
	v_lshlrev_b64 v[226:227], 11, v[228:229]
	v_lshl_add_u64 v[226:227], v[20:21], 0, v[226:227]
	global_load_ushort v210, v[226:227], off
	v_add_u32_e32 v228, 1, v228
	v_lshlrev_b64 v[226:227], 11, v[228:229]
	v_lshl_add_u64 v[226:227], v[20:21], 0, v[226:227]
	global_load_ushort v211, v[226:227], off
	v_add_u32_e32 v228, 1, v228
	v_lshlrev_b64 v[226:227], 11, v[228:229]
	v_lshl_add_u64 v[226:227], v[20:21], 0, v[226:227]
	global_load_ushort v212, v[226:227], off
	v_add_u32_e32 v228, s98, v95
	v_lshl_or_b32 v227, v228, 11, v97
	global_load_ushort v213, v227, s[68:69]
	v_add_u32_e32 v227, 0x800, v227
	global_load_ushort v214, v227, s[68:69]
	v_add_u32_e32 v227, 0x800, v227
	global_load_ushort v215, v227, s[68:69]
	v_add_u32_e32 v227, 0x800, v227
	global_load_ushort v216, v227, s[68:69]
	v_add_u32_e32 v227, 0x800, v227
	global_load_ushort v217, v227, s[68:69]
	v_add_u32_e32 v227, 0x800, v227
	global_load_ushort v218, v227, s[68:69]
	v_add_u32_e32 v227, 0x800, v227
	global_load_ushort v219, v227, s[68:69]
	v_add_u32_e32 v227, 0x800, v227
	global_load_ushort v220, v227, s[68:69]
.Llru_nopf:
	ds_read_b128 v[0:3], v47
	ds_read_b128 v[4:7], v57 offset:17408
	ds_read_b128 v[8:11], v57 offset:34816
	ds_read_b128 v[12:15], v59 offset:17408
	ds_read_b128 v[182:185], v59 offset:34816
	s_waitcnt lgkmcnt(3)
	v_mfma_f32_16x16x32_bf16 v[4:7], v[0:3], v[4:7], 0
	s_cmp_eq_u32 s61, 0
	s_cselect_b64 s[0:1], -1, 0
	s_and_b64 s[58:59], s[0:1], s[16:17]
	s_waitcnt lgkmcnt(2)
	v_mfma_f32_16x16x32_bf16 v[8:11], v[0:3], v[8:11], 0
	s_and_b32 s96, s96, 64
	s_waitcnt lgkmcnt(1)
	v_mfma_f32_16x16x32_bf16 v[12:15], v[0:3], v[12:15], 0
	s_waitcnt lgkmcnt(0)
	v_mfma_f32_16x16x32_bf16 v[0:3], v[0:3], v[182:185], 0
	ds_read_b128 v[182:185], v47 offset:64
	ds_read_b128 v[186:189], v57 offset:17472
	ds_read_b128 v[190:193], v57 offset:34880
	s_waitcnt lgkmcnt(1)
	v_mfma_f32_16x16x32_bf16 v[4:7], v[182:185], v[186:189], v[4:7]
	s_waitcnt lgkmcnt(0)
	v_mfma_f32_16x16x32_bf16 v[8:11], v[182:185], v[190:193], v[8:11]
	ds_read_b128 v[186:189], v59 offset:17472
	ds_read_b128 v[190:193], v59 offset:34880
	s_waitcnt lgkmcnt(1)
	v_mfma_f32_16x16x32_bf16 v[12:15], v[182:185], v[186:189], v[12:15]
	s_waitcnt lgkmcnt(0)
	v_mfma_f32_16x16x32_bf16 v[0:3], v[182:185], v[190:193], v[0:3]
	ds_read_b128 v[182:185], v47 offset:128
	ds_read_b128 v[186:189], v57 offset:17536
	ds_read_b128 v[190:193], v57 offset:34944
	s_waitcnt lgkmcnt(1)
	v_mfma_f32_16x16x32_bf16 v[4:7], v[182:185], v[186:189], v[4:7]
	s_waitcnt lgkmcnt(0)
	v_mfma_f32_16x16x32_bf16 v[8:11], v[182:185], v[190:193], v[8:11]
	ds_read_b128 v[186:189], v59 offset:17536
	ds_read_b128 v[190:193], v59 offset:34944
	s_waitcnt lgkmcnt(1)
; __device__ __forceinline__ float sigm(float x) { return __builtin_amdgcn_rcpf(1.f + __expf(-x)); }
; __device__ __forceinline__ void lru_item(LAS unsigned char* lds, int item, const bf16_t* XB, const bf16_t* GB, const float* conv_w, const float* conv_b, const bf16_t* WLA, const bf16_t* WLX,
;                                          const float* ba, const float* bx, const float* lam, bf16_t* YAB) {
;     ...
; #pragma unroll
;             for (int c2 = 0; c2 < 2; ++c2)
; #pragma unroll
;                 for (int j = 0; j < 4; ++j) {
;                     const int s = st * 16 + quad * 4 + j, cc = (ct0 + c2) * 16 + l15;
;                     const float r = sigm(ar[c2][j] + bav[c2]), ig = sigm(ai[c2][j] + bxv[c2]);
;                     const float la = 8.f * r * lsl[c2];
;                     const float a = __expf(la);
;                     float mult = sqrtf(fmaxf(-expm1f(2.f * la), 0.f));
;                     if (c == 0 && s == 0) mult = 1.f;
;                     AA[s * 65 + cc] = a; UU[s * 65 + cc] = XCF[s * 65 + cc] * ig * mult;
;                 }
	v_mfma_f32_16x16x32_bf16 v[186:189], v[182:185], v[186:189], v[12:15]
	s_waitcnt lgkmcnt(0)
	v_mfma_f32_16x16x32_bf16 v[0:3], v[182:185], v[190:193], v[0:3]
	ds_read_b128 v[182:185], v47 offset:192
	ds_read_b128 v[12:15], v57 offset:17600
	ds_read_b128 v[190:193], v57 offset:35008
	s_waitcnt lgkmcnt(1)
	v_mfma_f32_16x16x32_bf16 v[12:15], v[182:185], v[12:15], v[4:7]
	s_waitcnt lgkmcnt(0)
	v_mfma_f32_16x16x32_bf16 v[8:11], v[182:185], v[190:193], v[8:11]
	s_nop 5
	v_add_f32_e32 v12, v91, v12
	v_mul_f32_e32 v12, 0xbfb8aa3b, v12
	ds_read_b128 v[4:7], v59 offset:17600
	ds_read_b128 v[190:193], v59 offset:35008
	v_exp_f32_e32 v12, v12
	v_add_f32_e32 v8, v92, v8
	v_mul_f32_e32 v8, 0xbfb8aa3b, v8
	v_exp_f32_e32 v8, v8
	v_add_f32_e32 v12, 1.0, v12
	s_waitcnt lgkmcnt(1)
	v_mfma_f32_16x16x32_bf16 v[4:7], v[182:185], v[4:7], v[186:189]
	v_add_f32_e32 v8, 1.0, v8
	v_rcp_f32_e32 v8, v8
	s_waitcnt lgkmcnt(0)
	v_mfma_f32_16x16x32_bf16 v[0:3], v[182:185], v[190:193], v[0:3]
	v_rcp_f32_e32 v183, v12
	ds_read_b32 v12, v63 offset:52224
	s_nop 1
	v_add_f32_e32 v4, v93, v4
	v_mul_f32_e32 v4, 0xbfb8aa3b, v4
	v_exp_f32_e32 v4, v4
	s_nop 0
	v_add_f32_e32 v0, v94, v0
	s_waitcnt lgkmcnt(0)
	v_mul_f32_e32 v181, v12, v8
	v_add_f32_e32 v8, v91, v13
	v_mul_f32_e32 v8, 0xbfb8aa3b, v8
	v_exp_f32_e32 v8, v8
	v_mul_f32_e32 v0, 0xbfb8aa3b, v0
	v_exp_f32_e32 v0, v0
	v_add_f32_e32 v4, 1.0, v4
	v_add_f32_e32 v8, 1.0, v8
	v_rcp_f32_e32 v182, v8
	v_add_f32_e32 v8, v92, v9
	v_mul_f32_e32 v8, 0xbfb8aa3b, v8
	v_exp_f32_e32 v8, v8
	v_add_f32_e32 v0, 1.0, v0
	v_rcp_f32_e32 v0, v0
	v_add_f32_e32 v8, 1.0, v8
	v_rcp_f32_e32 v184, v8
	v_pk_mul_f32 v[8:9], v[182:183], s[50:51] op_sel_hi:[1,0]
	s_nop 0
	v_pk_mul_f32 v[8:9], v[8:9], v[24:25]
	s_nop 0
	v_mul_f32_e32 v12, 0x3fb8aa3b, v9
	v_exp_f32_e32 v182, v12
	v_pk_add_f32 v[12:13], v[8:9], v[8:9]
	v_mul_f32_e32 v8, 0x3fb8aa3b, v8
	v_mul_f32_e32 v9, 0x3fb8aa3b, v13
	v_rndne_f32_e32 v9, v9
	v_fmamk_f32 v183, v9, 0xbf317218, v13
	v_fmac_f32_e32 v183, 0x3102e308, v9
	v_fmamk_f32 v185, v183, 0x395133b1, v152
	v_cmp_eq_f32_e64 s[0:1], s66, v9
	v_cvt_i32_f32_e32 v9, v9
	v_fmaak_f32 v185, v183, v185, 0x3c0887f9
	v_fmaak_f32 v185, v183, v185, 0x3d2aaa81
	v_fmaak_f32 v185, v183, v185, 0x3e2aaaab
	v_fma_f32 v185, v183, v185, 0.5
	v_ldexp_f32 v9, 1.0, v9
	v_mul_f32_e32 v185, v183, v185
	v_cndmask_b32_e64 v9, v9, v164, s[0:1]
	v_fmac_f32_e32 v183, v183, v185
	v_add_f32_e32 v185, -1.0, v9
	v_fmac_f32_e32 v185, v9, v183
	v_add_f32_e32 v9, v185, v185
	v_cndmask_b32_e64 v9, v185, v9, s[0:1]
	v_max_f32_e64 v9, -v9, 0
	v_cmp_gt_f32_e64 s[0:1], s67, v9
	v_mul_f32_e32 v183, 0x4f800000, v9
	v_exp_f32_e32 v8, v8
	v_cndmask_b32_e64 v9, v9, v183, s[0:1]
	v_sqrt_f32_e32 v183, v9
	ds_write_b32 v61, v182
	v_add_u32_e32 v185, -1, v183
	v_fma_f32 v186, -v185, v183, v9
	v_cmp_ge_f32_e64 s[38:39], 0, v186
	v_add_u32_e32 v186, 1, v183
	s_nop 0
	v_cndmask_b32_e64 v185, v183, v185, s[38:39]
	v_fma_f32 v183, -v186, v183, v9
	v_cmp_lt_f32_e64 s[38:39], 0, v183
	s_nop 1
	v_cndmask_b32_e64 v183, v185, v186, s[38:39]
	v_mul_f32_e32 v185, 0x37800000, v183
	v_cndmask_b32_e64 v183, v183, v185, s[0:1]
	v_cmp_class_f32_e64 s[0:1], v9, v153
	s_nop 1
	v_cndmask_b32_e64 v9, v183, v9, s[0:1]
	v_cmp_nlt_f32_e64 s[0:1], s40, v13
	s_nop 1
	v_cndmask_b32_e64 v9, 0, v9, s[0:1]
	v_cmp_gt_f32_e64 s[0:1], s46, v13
	s_or_b64 s[0:1], s[58:59], s[0:1]
	s_nop 0
	v_cndmask_b32_e64 v9, v9, 1.0, s[0:1]
	v_mul_f32_e32 v9, v181, v9
	ds_write_b32 v65, v9
	v_mul_f32_e32 v9, 0x3fb8aa3b, v12
	v_rndne_f32_e32 v9, v9
	v_fmamk_f32 v13, v9, 0xbf317218, v12
	v_fmac_f32_e32 v13, 0x3102e308, v9
	v_fmamk_f32 v181, v13, 0x395133b1, v152
	v_cmp_eq_f32_e64 s[0:1], s66, v9
	v_cvt_i32_f32_e32 v9, v9
	v_fmaak_f32 v181, v13, v181, 0x3c0887f9
	v_fmaak_f32 v181, v13, v181, 0x3d2aaa81
	v_fmaak_f32 v181, v13, v181, 0x3e2aaaab
	v_fma_f32 v181, v13, v181, 0.5
	v_ldexp_f32 v9, 1.0, v9
	v_mul_f32_e32 v181, v13, v181
	v_cndmask_b32_e64 v9, v9, v164, s[0:1]
	v_fmac_f32_e32 v13, v13, v181
	v_add_f32_e32 v181, -1.0, v9
	v_fmac_f32_e32 v181, v9, v13
	v_add_f32_e32 v9, v181, v181
	v_cndmask_b32_e64 v9, v181, v9, s[0:1]
	v_max_f32_e64 v9, -v9, 0
	v_cmp_gt_f32_e64 s[0:1], s67, v9
	v_mul_f32_e32 v13, 0x4f800000, v9
	ds_write_b32 v67, v8
	v_cndmask_b32_e64 v9, v9, v13, s[0:1]
	v_sqrt_f32_e32 v13, v9
	ds_read_b32 v8, v63 offset:52484
	v_add_u32_e32 v181, -1, v13
	v_fma_f32 v182, -v181, v13, v9
	v_cmp_ge_f32_e64 s[38:39], 0, v182
	v_add_u32_e32 v182, 1, v13
	s_waitcnt lgkmcnt(0)
	v_mul_f32_e32 v8, v184, v8
	v_cndmask_b32_e64 v181, v13, v181, s[38:39]
	v_fma_f32 v13, -v182, v13, v9
	v_cmp_lt_f32_e64 s[38:39], 0, v13
	s_nop 1
	v_cndmask_b32_e64 v13, v181, v182, s[38:39]
	v_mul_f32_e32 v181, 0x37800000, v13
	v_cndmask_b32_e64 v13, v13, v181, s[0:1]
	v_cmp_class_f32_e64 s[0:1], v9, v153
	s_nop 1
	v_cndmask_b32_e64 v9, v13, v9, s[0:1]
	v_cmp_nlt_f32_e64 s[0:1], s40, v12
	s_nop 1
	v_cndmask_b32_e64 v9, 0, v9, s[0:1]
	v_cmp_ngt_f32_e64 s[0:1], s46, v12
	s_nop 1
	v_cndmask_b32_e64 v9, 1.0, v9, s[0:1]
	v_mul_f32_e32 v8, v8, v9
	ds_write_b32 v69, v8
	v_add_f32_e32 v8, v91, v14
	v_mul_f32_e32 v8, 0xbfb8aa3b, v8
	v_exp_f32_e32 v8, v8
	s_nop 0
	v_add_f32_e32 v8, 1.0, v8
	v_rcp_f32_e32 v9, v8
	v_add_f32_e32 v8, v92, v10
	v_mul_f32_e32 v8, 0xbfb8aa3b, v8
	v_exp_f32_e32 v8, v8
	ds_read_b32 v10, v63 offset:52744
	v_add_f32_e32 v8, 1.0, v8
	v_rcp_f32_e32 v8, v8
	s_waitcnt lgkmcnt(0)
; __device__ __forceinline__ float sigm(float x) { return __builtin_amdgcn_rcpf(1.f + __expf(-x)); }
; __device__ __forceinline__ void lru_item(LAS unsigned char* lds, int item, const bf16_t* XB, const bf16_t* GB, const float* conv_w, const float* conv_b, const bf16_t* WLA, const bf16_t* WLX,
;                                          const float* ba, const float* bx, const float* lam, bf16_t* YAB) {
;     ...
; #pragma unroll
;             for (int c2 = 0; c2 < 2; ++c2)
; #pragma unroll
;                 for (int j = 0; j < 4; ++j) {
;                     const int s = st * 16 + quad * 4 + j, cc = (ct0 + c2) * 16 + l15;
;                     const float r = sigm(ar[c2][j] + bav[c2]), ig = sigm(ai[c2][j] + bxv[c2]);
;                     const float la = 8.f * r * lsl[c2];
;                     const float a = __expf(la);
;                     float mult = sqrtf(fmaxf(-expm1f(2.f * la), 0.f));
;                     if (c == 0 && s == 0) mult = 1.f;
;                     AA[s * 65 + cc] = a; UU[s * 65 + cc] = XCF[s * 65 + cc] * ig * mult;
;                 }
	v_mul_f32_e32 v12, v8, v10
	v_add_f32_e32 v8, v91, v15
	v_mul_f32_e32 v8, 0xbfb8aa3b, v8
	v_exp_f32_e32 v8, v8
	v_add_f32_e32 v10, v92, v11
	v_mul_f32_e32 v10, 0xbfb8aa3b, v10
	v_exp_f32_e32 v10, v10
	v_add_f32_e32 v8, 1.0, v8
	v_rcp_f32_e32 v8, v8
	v_add_f32_e32 v10, 1.0, v10
	v_rcp_f32_e32 v13, v10
	v_pk_mul_f32 v[8:9], v[8:9], s[50:51] op_sel_hi:[1,0]
	s_nop 0
	v_pk_mul_f32 v[8:9], v[8:9], v[24:25]
	s_nop 0
	v_mul_f32_e32 v10, 0x3fb8aa3b, v9
	v_exp_f32_e32 v14, v10
	v_pk_add_f32 v[10:11], v[8:9], v[8:9]
	v_mul_f32_e32 v8, 0x3fb8aa3b, v8
	v_mul_f32_e32 v9, 0x3fb8aa3b, v11
	v_rndne_f32_e32 v9, v9
	v_fmamk_f32 v15, v9, 0xbf317218, v11
	v_fmac_f32_e32 v15, 0x3102e308, v9
	v_fmamk_f32 v181, v15, 0x395133b1, v152
	v_cmp_eq_f32_e64 s[0:1], s66, v9
	v_cvt_i32_f32_e32 v9, v9
	v_fmaak_f32 v181, v15, v181, 0x3c0887f9
	v_fmaak_f32 v181, v15, v181, 0x3d2aaa81
	v_fmaak_f32 v181, v15, v181, 0x3e2aaaab
	v_fma_f32 v181, v15, v181, 0.5
	v_ldexp_f32 v9, 1.0, v9
	v_mul_f32_e32 v181, v15, v181
	v_cndmask_b32_e64 v9, v9, v164, s[0:1]
	v_fmac_f32_e32 v15, v15, v181
	v_add_f32_e32 v181, -1.0, v9
	v_fmac_f32_e32 v181, v9, v15
	v_add_f32_e32 v9, v181, v181
	v_cndmask_b32_e64 v9, v181, v9, s[0:1]
	v_max_f32_e64 v9, -v9, 0
	v_cmp_gt_f32_e64 s[0:1], s67, v9
	v_mul_f32_e32 v15, 0x4f800000, v9
	v_exp_f32_e32 v8, v8
	v_cndmask_b32_e64 v9, v9, v15, s[0:1]
	v_sqrt_f32_e32 v15, v9
	ds_write_b32 v71, v14
	v_add_u32_e32 v181, -1, v15
	v_fma_f32 v182, -v181, v15, v9
	v_cmp_ge_f32_e64 s[38:39], 0, v182
	v_add_u32_e32 v182, 1, v15
	s_nop 0
	v_cndmask_b32_e64 v181, v15, v181, s[38:39]
	v_fma_f32 v15, -v182, v15, v9
	v_cmp_lt_f32_e64 s[38:39], 0, v15
	s_nop 1
	v_cndmask_b32_e64 v15, v181, v182, s[38:39]
	v_mul_f32_e32 v181, 0x37800000, v15
	v_cndmask_b32_e64 v15, v15, v181, s[0:1]
	v_cmp_class_f32_e64 s[0:1], v9, v153
	s_nop 1
	v_cndmask_b32_e64 v9, v15, v9, s[0:1]
	v_cmp_nlt_f32_e64 s[0:1], s40, v11
	s_nop 1
	v_cndmask_b32_e64 v9, 0, v9, s[0:1]
	v_cmp_ngt_f32_e64 s[0:1], s46, v11
	s_nop 1
	v_cndmask_b32_e64 v9, 1.0, v9, s[0:1]
	v_mul_f32_e32 v9, v12, v9
	ds_write_b32 v73, v9
	v_mul_f32_e32 v9, 0x3fb8aa3b, v10
	v_rndne_f32_e32 v9, v9
	v_fmamk_f32 v11, v9, 0xbf317218, v10
	v_fmac_f32_e32 v11, 0x3102e308, v9
	v_fmamk_f32 v12, v11, 0x395133b1, v152
	v_cmp_eq_f32_e64 s[0:1], s66, v9
	v_cvt_i32_f32_e32 v9, v9
	v_fmaak_f32 v12, v11, v12, 0x3c0887f9
	v_fmaak_f32 v12, v11, v12, 0x3d2aaa81
	v_fmaak_f32 v12, v11, v12, 0x3e2aaaab
	v_fma_f32 v12, v11, v12, 0.5
	v_ldexp_f32 v9, 1.0, v9
	v_mul_f32_e32 v12, v11, v12
	v_cndmask_b32_e64 v9, v9, v164, s[0:1]
	v_fmac_f32_e32 v11, v11, v12
	v_add_f32_e32 v12, -1.0, v9
	v_fmac_f32_e32 v12, v9, v11
	v_add_f32_e32 v9, v12, v12
	v_cndmask_b32_e64 v9, v12, v9, s[0:1]
	v_max_f32_e64 v9, -v9, 0
	v_cmp_gt_f32_e64 s[0:1], s67, v9
	v_mul_f32_e32 v11, 0x4f800000, v9
	ds_write_b32 v75, v8
	v_cndmask_b32_e64 v9, v9, v11, s[0:1]
	v_sqrt_f32_e32 v11, v9
	ds_read_b32 v8, v63 offset:53004
	v_add_u32_e32 v12, -1, v11
	v_fma_f32 v14, -v12, v11, v9
	v_cmp_ge_f32_e64 s[38:39], 0, v14
	v_add_u32_e32 v14, 1, v11
	s_waitcnt lgkmcnt(0)
	v_mul_f32_e32 v8, v13, v8
	v_cndmask_b32_e64 v12, v11, v12, s[38:39]
	v_fma_f32 v11, -v14, v11, v9
	v_cmp_lt_f32_e64 s[38:39], 0, v11
	s_nop 1
	v_cndmask_b32_e64 v11, v12, v14, s[38:39]
	v_mul_f32_e32 v12, 0x37800000, v11
	v_cndmask_b32_e64 v11, v11, v12, s[0:1]
	v_cmp_class_f32_e64 s[0:1], v9, v153
	s_nop 1
	v_cndmask_b32_e64 v9, v11, v9, s[0:1]
	v_cmp_nlt_f32_e64 s[0:1], s40, v10
	s_nop 1
	v_cndmask_b32_e64 v9, 0, v9, s[0:1]
	v_cmp_ngt_f32_e64 s[0:1], s46, v10
	s_nop 1
	v_cndmask_b32_e64 v9, 1.0, v9, s[0:1]
	v_mul_f32_e32 v8, v8, v9
	ds_write_b32 v77, v8
	v_rcp_f32_e32 v9, v4
	ds_read_b32 v4, v63 offset:52288
	s_waitcnt lgkmcnt(0)
	v_mul_f32_e32 v10, v0, v4
	v_add_f32_e32 v0, v93, v5
	v_mul_f32_e32 v0, 0xbfb8aa3b, v0
	v_exp_f32_e32 v0, v0
	s_nop 0
	v_add_f32_e32 v0, 1.0, v0
	v_rcp_f32_e32 v8, v0
	v_add_f32_e32 v0, v94, v1
	v_mul_f32_e32 v0, 0xbfb8aa3b, v0
	v_exp_f32_e32 v0, v0
	s_nop 0
	v_add_f32_e32 v0, 1.0, v0
	v_rcp_f32_e32 v11, v0
	v_pk_mul_f32 v[0:1], v[8:9], s[50:51] op_sel_hi:[1,0]
	s_nop 0
	v_pk_mul_f32 v[0:1], v[0:1], v[22:23]
	s_nop 0
	v_mul_f32_e32 v4, 0x3fb8aa3b, v1
	v_exp_f32_e32 v8, v4
	v_pk_add_f32 v[4:5], v[0:1], v[0:1]
	v_mul_f32_e32 v0, 0x3fb8aa3b, v0
	v_mul_f32_e32 v1, 0x3fb8aa3b, v5
	v_rndne_f32_e32 v1, v1
	v_fmamk_f32 v9, v1, 0xbf317218, v5
	v_fmac_f32_e32 v9, 0x3102e308, v1
	v_fmamk_f32 v12, v9, 0x395133b1, v152
	v_cmp_eq_f32_e64 s[0:1], s66, v1
	v_cvt_i32_f32_e32 v1, v1
	v_fmaak_f32 v12, v9, v12, 0x3c0887f9
	v_fmaak_f32 v12, v9, v12, 0x3d2aaa81
	v_fmaak_f32 v12, v9, v12, 0x3e2aaaab
	v_fma_f32 v12, v9, v12, 0.5
	v_ldexp_f32 v1, 1.0, v1
	v_mul_f32_e32 v12, v9, v12
	v_cndmask_b32_e64 v1, v1, v164, s[0:1]
	v_fmac_f32_e32 v9, v9, v12
	v_add_f32_e32 v12, -1.0, v1
	v_fmac_f32_e32 v12, v1, v9
	v_add_f32_e32 v1, v12, v12
	v_cndmask_b32_e64 v1, v12, v1, s[0:1]
	v_max_f32_e64 v1, -v1, 0
	v_cmp_gt_f32_e64 s[0:1], s67, v1
	v_mul_f32_e32 v9, 0x4f800000, v1
	ds_write_b32 v79, v8
	v_cndmask_b32_e64 v1, v1, v9, s[0:1]
	v_sqrt_f32_e32 v9, v1
	v_exp_f32_e32 v0, v0
	v_add_u32_e32 v12, -1, v9
	v_fma_f32 v13, -v12, v9, v1
	v_cmp_ge_f32_e64 s[38:39], 0, v13
	v_add_u32_e32 v13, 1, v9
	s_nop 0
	v_cndmask_b32_e64 v12, v9, v12, s[38:39]
	v_fma_f32 v9, -v13, v9, v1
	v_cmp_lt_f32_e64 s[38:39], 0, v9
	s_nop 1
	v_cndmask_b32_e64 v9, v12, v13, s[38:39]
	v_mul_f32_e32 v12, 0x37800000, v9
	v_cndmask_b32_e64 v9, v9, v12, s[0:1]
	v_cmp_class_f32_e64 s[0:1], v1, v153
	s_nop 1
	v_cndmask_b32_e64 v1, v9, v1, s[0:1]
	v_cmp_nlt_f32_e64 s[0:1], s40, v5
	s_nop 1
	v_cndmask_b32_e64 v1, 0, v1, s[0:1]
	v_cmp_gt_f32_e64 s[0:1], s46, v5
	s_or_b64 s[0:1], s[58:59], s[0:1]
	s_nop 0
	v_cndmask_b32_e64 v1, v1, 1.0, s[0:1]
	v_mul_f32_e32 v1, v10, v1
	ds_write_b32 v85, v1
	v_mul_f32_e32 v1, 0x3fb8aa3b, v4
	v_rndne_f32_e32 v1, v1
	v_fmamk_f32 v5, v1, 0xbf317218, v4
	v_fmac_f32_e32 v5, 0x3102e308, v1
	v_fmamk_f32 v8, v5, 0x395133b1, v152
	v_cmp_eq_f32_e64 s[0:1], s66, v1
	v_cvt_i32_f32_e32 v1, v1
	v_fmaak_f32 v8, v5, v8, 0x3c0887f9
	v_fmaak_f32 v8, v5, v8, 0x3d2aaa81
	v_fmaak_f32 v8, v5, v8, 0x3e2aaaab
	v_fma_f32 v8, v5, v8, 0.5
	v_ldexp_f32 v1, 1.0, v1
	v_mul_f32_e32 v8, v5, v8
	v_cndmask_b32_e64 v1, v1, v164, s[0:1]
	v_fmac_f32_e32 v5, v5, v8
	v_add_f32_e32 v8, -1.0, v1
	v_fmac_f32_e32 v8, v1, v5
	v_add_f32_e32 v1, v8, v8
	v_cndmask_b32_e64 v1, v8, v1, s[0:1]
	v_max_f32_e64 v1, -v1, 0
	v_cmp_gt_f32_e64 s[0:1], s67, v1
	v_mul_f32_e32 v5, 0x4f800000, v1
	ds_write_b32 v87, v0
	v_cndmask_b32_e64 v1, v1, v5, s[0:1]
	v_sqrt_f32_e32 v5, v1
	ds_read_b32 v0, v89 offset:52484
	v_add_u32_e32 v8, -1, v5
	v_fma_f32 v9, -v8, v5, v1
	v_cmp_ge_f32_e64 s[38:39], 0, v9
	v_add_u32_e32 v9, 1, v5
	s_waitcnt lgkmcnt(0)
; __device__ __forceinline__ float sigm(float x) { return __builtin_amdgcn_rcpf(1.f + __expf(-x)); }
; __device__ __forceinline__ void lru_item(LAS unsigned char* lds, int item, const bf16_t* XB, const bf16_t* GB, const float* conv_w, const float* conv_b, const bf16_t* WLA, const bf16_t* WLX,
;                                          const float* ba, const float* bx, const float* lam, bf16_t* YAB) {
;     ...
;             for (int c2 = 0; c2 < 2; ++c2)
; #pragma unroll
;                 for (int j = 0; j < 4; ++j) {
;                     const int s = st * 16 + quad * 4 + j, cc = (ct0 + c2) * 16 + l15;
;                     const float r = sigm(ar[c2][j] + bav[c2]), ig = sigm(ai[c2][j] + bxv[c2]);
;                     const float la = 8.f * r * lsl[c2];
;                     const float a = __expf(la);
;                     float mult = sqrtf(fmaxf(-expm1f(2.f * la), 0.f));
;                     if (c == 0 && s == 0) mult = 1.f;
;                     AA[s * 65 + cc] = a; UU[s * 65 + cc] = XCF[s * 65 + cc] * ig * mult;
;                 }
;         }
;         __syncthreads();
;         float a8[8], u8[8];
; #pragma unroll
;         for (int i = 0; i < 8; ++i) { a8[i] = AA[(g * 8 + i) * 65 + cl]; u8[i] = UU[(g * 8 + i) * 65 + cl]; }
;         { float pa = 1.f, ph = 0.f;
; #pragma unroll
;           for (int i = 0; i < 8; ++i) { pa *= a8[i]; ph = a8[i] * ph + u8[i]; }
;           GA[g * 64 + cl] = pa; GH[g * 64 + cl] = ph; }
;         __syncthreads();
;         float hh = HC[(c & 1) * 64 + cl];
;         for (int g2 = 0; g2 < g; ++g2) hh = GA[g2 * 64 + cl] * hh + GH[g2 * 64 + cl];
	v_mul_f32_e32 v0, v11, v0
	v_cndmask_b32_e64 v8, v5, v8, s[38:39]
	v_fma_f32 v5, -v9, v5, v1
	v_cmp_lt_f32_e64 s[38:39], 0, v5
	s_nop 1
	v_cndmask_b32_e64 v5, v8, v9, s[38:39]
	v_mul_f32_e32 v8, 0x37800000, v5
	v_cndmask_b32_e64 v5, v5, v8, s[0:1]
	v_cmp_class_f32_e64 s[0:1], v1, v153
	s_nop 1
	v_cndmask_b32_e64 v1, v5, v1, s[0:1]
	v_cmp_nlt_f32_e64 s[0:1], s40, v4
	s_nop 1
	v_cndmask_b32_e64 v1, 0, v1, s[0:1]
	v_cmp_ngt_f32_e64 s[0:1], s46, v4
	s_nop 1
	v_cndmask_b32_e64 v1, 1.0, v1, s[0:1]
	v_mul_f32_e32 v0, v0, v1
	ds_write_b32 v104, v0
	v_add_f32_e32 v0, v93, v6
	v_mul_f32_e32 v0, 0xbfb8aa3b, v0
	v_exp_f32_e32 v0, v0
	s_nop 0
	v_add_f32_e32 v0, 1.0, v0
	v_rcp_f32_e32 v1, v0
	v_add_f32_e32 v0, v94, v2
	v_mul_f32_e32 v0, 0xbfb8aa3b, v0
	v_exp_f32_e32 v0, v0
	ds_read_b32 v2, v89 offset:52744
	v_add_f32_e32 v0, 1.0, v0
	v_rcp_f32_e32 v0, v0
	s_waitcnt lgkmcnt(0)
	v_mul_f32_e32 v4, v0, v2
	v_add_f32_e32 v0, v93, v7
	v_mul_f32_e32 v0, 0xbfb8aa3b, v0
	v_exp_f32_e32 v0, v0
	v_add_f32_e32 v2, v94, v3
	v_mul_f32_e32 v2, 0xbfb8aa3b, v2
	v_exp_f32_e32 v2, v2
	v_add_f32_e32 v0, 1.0, v0
	v_rcp_f32_e32 v0, v0
	v_add_f32_e32 v2, 1.0, v2
	v_rcp_f32_e32 v5, v2
	v_pk_mul_f32 v[0:1], v[0:1], s[50:51] op_sel_hi:[1,0]
	s_nop 0
	v_pk_mul_f32 v[0:1], v[0:1], v[22:23]
	s_nop 0
	v_mul_f32_e32 v2, 0x3fb8aa3b, v1
	v_exp_f32_e32 v6, v2
	v_pk_add_f32 v[2:3], v[0:1], v[0:1]
	v_mul_f32_e32 v0, 0x3fb8aa3b, v0
	v_mul_f32_e32 v1, 0x3fb8aa3b, v3
	v_rndne_f32_e32 v1, v1
	v_fmamk_f32 v7, v1, 0xbf317218, v3
	v_fmac_f32_e32 v7, 0x3102e308, v1
	v_fmamk_f32 v8, v7, 0x395133b1, v152
	v_cmp_eq_f32_e64 s[0:1], s66, v1
	v_cvt_i32_f32_e32 v1, v1
	v_fmaak_f32 v8, v7, v8, 0x3c0887f9
	v_fmaak_f32 v8, v7, v8, 0x3d2aaa81
	v_fmaak_f32 v8, v7, v8, 0x3e2aaaab
	v_fma_f32 v8, v7, v8, 0.5
	v_ldexp_f32 v1, 1.0, v1
	v_mul_f32_e32 v8, v7, v8
	v_cndmask_b32_e64 v1, v1, v164, s[0:1]
	v_fmac_f32_e32 v7, v7, v8
	v_add_f32_e32 v8, -1.0, v1
	v_fmac_f32_e32 v8, v1, v7
	v_add_f32_e32 v1, v8, v8
	v_cndmask_b32_e64 v1, v8, v1, s[0:1]
	v_max_f32_e64 v1, -v1, 0
	v_cmp_gt_f32_e64 s[0:1], s67, v1
	v_mul_f32_e32 v7, 0x4f800000, v1
	v_exp_f32_e32 v0, v0
	v_cndmask_b32_e64 v1, v1, v7, s[0:1]
	v_sqrt_f32_e32 v7, v1
	ds_write_b32 v105, v6
	v_add_u32_e32 v8, -1, v7
	v_fma_f32 v9, -v8, v7, v1
	v_cmp_ge_f32_e64 s[38:39], 0, v9
	v_add_u32_e32 v9, 1, v7
	s_nop 0
	v_cndmask_b32_e64 v8, v7, v8, s[38:39]
	v_fma_f32 v7, -v9, v7, v1
	v_cmp_lt_f32_e64 s[38:39], 0, v7
	s_nop 1
	v_cndmask_b32_e64 v7, v8, v9, s[38:39]
	v_mul_f32_e32 v8, 0x37800000, v7
	v_cndmask_b32_e64 v7, v7, v8, s[0:1]
	v_cmp_class_f32_e64 s[0:1], v1, v153
	s_nop 1
	v_cndmask_b32_e64 v1, v7, v1, s[0:1]
	v_cmp_nlt_f32_e64 s[0:1], s40, v3
	s_nop 1
	v_cndmask_b32_e64 v1, 0, v1, s[0:1]
	v_cmp_ngt_f32_e64 s[0:1], s46, v3
	s_nop 1
	v_cndmask_b32_e64 v1, 1.0, v1, s[0:1]
	v_mul_f32_e32 v1, v4, v1
	ds_write_b32 v106, v1
	v_mul_f32_e32 v1, 0x3fb8aa3b, v2
	v_rndne_f32_e32 v1, v1
	v_fmamk_f32 v3, v1, 0xbf317218, v2
	v_fmac_f32_e32 v3, 0x3102e308, v1
	v_fmamk_f32 v4, v3, 0x395133b1, v152
	v_cmp_eq_f32_e64 s[0:1], s66, v1
	v_cvt_i32_f32_e32 v1, v1
	v_fmaak_f32 v4, v3, v4, 0x3c0887f9
	v_fmaak_f32 v4, v3, v4, 0x3d2aaa81
	v_fmaak_f32 v4, v3, v4, 0x3e2aaaab
	v_fma_f32 v4, v3, v4, 0.5
	v_ldexp_f32 v1, 1.0, v1
	v_mul_f32_e32 v4, v3, v4
	v_cndmask_b32_e64 v1, v1, v164, s[0:1]
	v_fmac_f32_e32 v3, v3, v4
	v_add_f32_e32 v4, -1.0, v1
	v_fmac_f32_e32 v4, v1, v3
	v_add_f32_e32 v1, v4, v4
	v_cndmask_b32_e64 v1, v4, v1, s[0:1]
	v_max_f32_e64 v1, -v1, 0
	v_cmp_gt_f32_e64 s[0:1], s67, v1
	v_mul_f32_e32 v3, 0x4f800000, v1
	ds_write_b32 v107, v0
	v_cndmask_b32_e64 v1, v1, v3, s[0:1]
	v_sqrt_f32_e32 v3, v1
	ds_read_b32 v0, v89 offset:53004
	v_add_u32_e32 v4, -1, v3
	v_fma_f32 v6, -v4, v3, v1
	v_cmp_ge_f32_e64 s[38:39], 0, v6
	v_add_u32_e32 v6, 1, v3
	s_waitcnt lgkmcnt(0)
	v_mul_f32_e32 v0, v5, v0
	v_cndmask_b32_e64 v4, v3, v4, s[38:39]
	v_fma_f32 v3, -v6, v3, v1
	v_cmp_lt_f32_e64 s[38:39], 0, v3
	s_nop 1
	v_cndmask_b32_e64 v3, v4, v6, s[38:39]
	v_mul_f32_e32 v4, 0x37800000, v3
	v_cndmask_b32_e64 v3, v3, v4, s[0:1]
	v_cmp_class_f32_e64 s[0:1], v1, v153
	s_nop 1
	v_cndmask_b32_e64 v1, v3, v1, s[0:1]
	v_cmp_nlt_f32_e64 s[0:1], s40, v2
	s_nop 1
	v_cndmask_b32_e64 v1, 0, v1, s[0:1]
	v_cmp_ngt_f32_e64 s[0:1], s46, v2
	s_nop 1
	v_cndmask_b32_e64 v1, 1.0, v1, s[0:1]
	v_mul_f32_e32 v0, v0, v1
	ds_write_b32 v108, v0
	s_waitcnt lgkmcnt(0)
	s_barrier
	ds_read_b32 v15, v109
	ds_read_b32 v13, v110
	ds_read_b32 v14, v111
	ds_read_b32 v11, v112
	ds_read_b32 v12, v113
	ds_read_b32 v9, v114
	ds_read_b32 v10, v115
	ds_read_b32 v7, v116
	ds_read_b32 v8, v117
	ds_read_b32 v5, v118
	ds_read_b32 v6, v119
	ds_read_b32 v3, v120
	ds_read_b32 v4, v121
	ds_read_b32 v1, v122
	ds_read_b32 v2, v123
	ds_read_b32 v0, v124
	s_waitcnt lgkmcnt(14)
	v_fma_f32 v181, 0, v15, v13
	s_waitcnt lgkmcnt(13)
	v_mul_f32_e32 v182, v15, v14
	s_waitcnt lgkmcnt(12)
	v_fma_f32 v181, v181, v14, v11
	s_waitcnt lgkmcnt(11)
	v_mul_f32_e32 v182, v182, v12
	s_waitcnt lgkmcnt(10)
	v_fma_f32 v181, v181, v12, v9
	s_waitcnt lgkmcnt(9)
	v_mul_f32_e32 v182, v182, v10
	s_waitcnt lgkmcnt(8)
	v_fma_f32 v181, v181, v10, v7
	s_waitcnt lgkmcnt(7)
	v_mul_f32_e32 v182, v182, v8
	s_waitcnt lgkmcnt(6)
	v_fma_f32 v181, v181, v8, v5
	s_waitcnt lgkmcnt(5)
	v_mul_f32_e32 v182, v182, v6
	s_waitcnt lgkmcnt(4)
	v_fma_f32 v181, v181, v6, v3
	s_waitcnt lgkmcnt(3)
	v_mul_f32_e32 v182, v182, v4
	s_waitcnt lgkmcnt(2)
	v_fma_f32 v181, v181, v4, v1
	s_waitcnt lgkmcnt(1)
	v_mul_f32_e32 v182, v182, v2
	s_waitcnt lgkmcnt(0)
	v_fma_f32 v181, v181, v2, v0
	ds_write_b32 v49, v182
	ds_write_b32 v51, v181
	v_lshl_add_u32 v181, s96, 2, v53
	s_waitcnt lgkmcnt(0)
	s_barrier
	ds_read_b32 v181, v181
	s_and_saveexec_b64 s[38:39], s[4:5]
	s_cbranch_execz .LBB0_679
	s_mov_b64 s[58:59], 0
	v_mov_b32_e32 v182, v146
	v_mov_b32_e32 v183, v31

; #define LAS __attribute__((address_space(3)))
; __device__ __forceinline__ unsigned cvt_pk_bf16(float lo, float hi) { f32x2_c v = {lo, hi}; bf16x2_c r = __builtin_convertvector(v, bf16x2_c); return __builtin_bit_cast(unsigned, r); }
; __device__ __forceinline__ bf16_t f2bf(float f) { return (bf16_t)(cvt_pk_bf16(f, 0.f) & 0xffffu); }
; __device__ __forceinline__ float bf2f(bf16_t b) { return __uint_as_float(((unsigned)b) << 16); }
; __device__ __forceinline__ void hgrn_item(LAS unsigned char* lds, int item, const bf16_t* QS, const float* LF, const bf16_t* KK, const bf16_t* VV, bf16_t* YAB) {
;     ...
;         for (int i = 0; i < 16; ++i) {
;             const float bb = pre + bl[i];
;             const float e1 = __expf(fminf(fmaxf(bb - mref, -80.f), 80.f)), e2 = __builtin_amdgcn_rcpf(e1);
;             const float q = bf2f(qv[i]), kx = bf2f(kv[i]);
;             const int s = part * 16 + i;
;             QT[s * 136 + k] = f2bf(q * e1); KT[s * 136 + k] = f2bf(kx * e2); QH[s * 136 + k] = f2bf(q * e1 * em); kd[i] = kx * e2 * ebm;
;         }
;         { u32x4 w0, w1;
;           w0.x = cvt_pk_bf16(kd[0], kd[1]); w0.y = cvt_pk_bf16(kd[2], kd[3]); w0.z = cvt_pk_bf16(kd[4], kd[5]); w0.w = cvt_pk_bf16(kd[6], kd[7]);
;           w1.x = cvt_pk_bf16(kd[8], kd[9]); w1.y = cvt_pk_bf16(kd[10], kd[11]); w1.z = cvt_pk_bf16(kd[12], kd[13]); w1.w = cvt_pk_bf16(kd[14], kd[15]);
;           *(LAS u32x4*)(KD + k * 72 + part * 16) = w0; *(LAS u32x4*)(KD + k * 72 + part * 16 + 8) = w1; }
;         if (part == 0) DD[k] = em * ebm;
.LBB0_701:
	s_or_b64 exec, exec, s[38:39]
	s_waitcnt lgkmcnt(0)
	v_mov_b32_e32 v226, v23
	v_mov_b32_e32 v227, v20
	v_mov_b32_e32 v23, v21
	s_add_u32 s98, s24, 0x35e40000
	s_addc_u32 s99, s25, 0
	global_load_dword v171, v102, s[98:99]
	v_pk_add_f32 v[20:21], v[226:227], v[22:23]
	v_add_f32_e32 v223, v223, v211
	v_mul_f32_e32 v22, 0x3fb8aa3b, v21
	v_exp_f32_e32 v213, v22
	s_add_u32 s98, s24, 0x35e41000
	s_addc_u32 s99, s25, 0
	global_load_dword v175, v102, s[98:99]
	v_add_f32_e32 v22, v224, v211
	v_sub_f32_e32 v22, v22, v21
	v_med3_f32 v22, v22, s2, v165
	v_mul_f32_e32 v22, 0x3fb8aa3b, v22
	s_add_u32 s98, s24, 0x35e42000
	s_addc_u32 s99, s25, 0
	global_load_dword v181, v102, s[98:99]
	v_exp_f32_e32 v23, v22
	v_sub_f32_e32 v223, v223, v21
	v_med3_f32 v223, v223, s2, v165
	v_mul_f32_e32 v223, 0x3fb8aa3b, v223
	s_add_u32 s98, s24, 0x35e43000
	s_addc_u32 s99, s25, 0
	global_load_dword v183, v102, s[98:99]
	v_lshlrev_b32_e32 v224, 16, v172
	v_exp_f32_e32 v223, v223
	v_rcp_f32_e32 v22, v23
	v_mul_f32_e32 v23, v23, v224
	s_add_u32 s98, s24, 0x35e44000
	s_addc_u32 s99, s25, 0
	global_load_dword v185, v102, s[98:99]
	v_cvt_pk_bf16_f32 v224, v23, s0
	v_mul_f32_e32 v23, v213, v23
	v_add_f32_e32 v20, v21, v20
	v_cvt_pk_bf16_f32 v23, v23, s0
	s_add_u32 s98, s24, 0x35e45000
	s_addc_u32 s99, s25, 0
	global_load_dword v187, v102, s[98:99]
	v_sub_f32_e32 v20, v20, v21
	ds_write_b16 v135, v23 offset:34816
	v_rcp_f32_e32 v23, v223
	v_add_f32_e32 v25, v25, v211
	s_add_u32 s98, s24, 0x35e46000
	s_addc_u32 s99, s25, 0
	global_load_dword v169, v102, s[98:99]
	v_mul_f32_e32 v20, 0x3fb8aa3b, v20
	v_sub_f32_e32 v25, v25, v21
	v_exp_f32_e32 v20, v20
	ds_write_b16 v135, v224
	s_add_u32 s98, s24, 0x35e47000
	s_addc_u32 s99, s25, 0
	global_load_dword v173, v102, s[98:99]
	v_lshlrev_b32_e32 v224, 16, v180
	v_med3_f32 v25, v25, s2, v165
	v_mul_f32_e32 v223, v223, v224
	v_and_b32_e32 v225, 0xffff0000, v81
	s_add_u32 s98, s24, 0x35e48000
	s_addc_u32 s99, s25, 0
	global_load_dword v188, v102, s[98:99]
	v_lshlrev_b32_e32 v224, 16, v81
	v_mul_f32_e32 v25, 0x3fb8aa3b, v25
	v_add_f32_e32 v24, v24, v211
	v_pk_mul_f32 v[224:225], v[22:23], v[224:225]
	s_add_u32 s98, s24, 0x35e49000
	s_addc_u32 s99, s25, 0
	global_load_dword v190, v102, s[98:99]
	v_exp_f32_e32 v25, v25
	v_sub_f32_e32 v24, v24, v21
	v_cvt_pk_bf16_f32 v226, v223, s0
	v_mul_f32_e32 v223, v213, v223
	s_add_u32 s98, s24, 0x35e4a000
	s_addc_u32 s99, s25, 0
	global_load_dword v192, v102, s[98:99]
	v_cvt_pk_bf16_f32 v22, v224, s0
	v_med3_f32 v24, v24, s2, v165
	v_cvt_pk_bf16_f32 v223, v223, s0
	ds_write_b16 v135, v22 offset:17408
	s_add_u32 s98, s24, 0x35e4b000
	s_addc_u32 s99, s25, 0
	global_load_dword v195, v102, s[98:99]
	v_pk_mul_f32 v[22:23], v[20:21], v[224:225] op_sel_hi:[0,1]
	v_cvt_pk_bf16_f32 v224, v225, s0
	v_mul_f32_e32 v24, 0x3fb8aa3b, v24
	ds_write_b16 v136, v226
	s_add_u32 s98, s24, 0x35e4c000
	s_addc_u32 s99, s25, 0
	global_load_dword v198, v102, s[98:99]
	ds_write_b16 v136, v224 offset:17408
	ds_write_b16 v136, v223 offset:34816
	v_lshlrev_b32_e32 v223, 16, v182
	v_exp_f32_e32 v24, v24
	s_add_u32 s98, s24, 0x35e4d000
	s_addc_u32 s99, s25, 0
	global_load_dword v201, v102, s[98:99]
	v_rcp_f32_e32 v224, v25
	v_mul_f32_e32 v25, v25, v223
	v_cvt_pk_bf16_f32 v223, v25, s0
	v_mul_f32_e32 v25, v213, v25
	s_add_u32 s98, s24, 0x35e4e000
	s_addc_u32 s99, s25, 0
	global_load_dword v197, v102, s[98:99]
	v_add_u32_e32 v226, v43, v55
	v_cvt_pk_bf16_f32 v25, v25, s0
	v_add_f32_e32 v222, v222, v211
	ds_write_b16 v226, v25 offset:35088
	s_add_u32 s98, s24, 0x35e4f000
	s_addc_u32 s99, s25, 0
	global_load_dword v202, v102, s[98:99]
	v_rcp_f32_e32 v225, v24
	v_lshlrev_b32_e32 v25, 16, v184
	v_sub_f32_e32 v222, v222, v21
	v_mul_f32_e32 v24, v24, v25
	s_add_u32 s98, s24, 0x1de20000
	s_addc_u32 s99, s25, 0
	global_load_ushort v172, v100, s[98:99]
	v_med3_f32 v222, v222, s2, v165
	ds_write_b16 v226, v223 offset:272
	v_cvt_pk_bf16_f32 v223, v24, s0
	v_mul_f32_e32 v24, v213, v24
	s_add_u32 s98, s24, 0x1de20000
	s_addc_u32 s99, s25, 0
	global_load_ushort v180, v100, s[98:99] offset:2048
	v_mul_f32_e32 v222, 0x3fb8aa3b, v222
	v_add_f32_e32 v221, v221, v211
	v_cvt_pk_bf16_f32 v227, v24, s0
	v_and_b32_e32 v25, 0xffff0000, v91
	s_add_u32 s98, s24, 0x21e20000
	s_addc_u32 s99, s25, 0
	global_load_ushort v81, v100, s[98:99]
	global_load_ushort v232, v100, s[98:99] offset:2048
	v_lshlrev_b32_e32 v24, 16, v91
	ds_write_b16 v226, v223 offset:544
	v_exp_f32_e32 v223, v222
	v_sub_f32_e32 v221, v221, v21
	s_add_u32 s98, s24, 0x1de21000
	s_addc_u32 s99, s25, 0
	global_load_ushort v182, v100, s[98:99]
	v_pk_mul_f32 v[224:225], v[224:225], v[24:25]
	v_med3_f32 v221, v221, s2, v165
	v_cvt_pk_bf16_f32 v24, v224, s0
	v_mul_f32_e32 v221, 0x3fb8aa3b, v221
	s_add_u32 s98, s24, 0x1de21000
	s_addc_u32 s99, s25, 0
	global_load_ushort v184, v100, s[98:99] offset:2048
	ds_write_b16 v226, v24 offset:17680
	v_pk_mul_f32 v[24:25], v[20:21], v[224:225] op_sel_hi:[0,1]
	v_cvt_pk_bf16_f32 v222, v225, s0
	v_lshlrev_b32_e32 v224, 16, v186
	s_add_u32 s98, s24, 0x21e21000
	s_addc_u32 s99, s25, 0
	global_load_ushort v91, v100, s[98:99]
	global_load_ushort v233, v100, s[98:99] offset:2048
	v_exp_f32_e32 v221, v221
	ds_write_b16 v226, v222 offset:17952
	ds_write_b16 v226, v227 offset:35360
	v_rcp_f32_e32 v222, v223
	s_add_u32 s98, s24, 0x1de22000
	s_addc_u32 s99, s25, 0
	global_load_ushort v186, v100, s[98:99]
	v_mul_f32_e32 v223, v223, v224
	v_cvt_pk_bf16_f32 v224, v223, s0
	v_mul_f32_e32 v223, v213, v223
	v_cvt_pk_bf16_f32 v223, v223, s0
	ds_write_b16 v226, v223 offset:35632
	v_rcp_f32_e32 v223, v221
	ds_write_b16 v226, v224 offset:816
	v_lshlrev_b32_e32 v224, 16, v168
; __device__ __forceinline__ bf16_t f2bf(float f) { return (bf16_t)(cvt_pk_bf16(f, 0.f) & 0xffffu); }
; __device__ __forceinline__ float bf2f(bf16_t b) { return __uint_as_float(((unsigned)b) << 16); }
; __device__ __forceinline__ void hgrn_item(LAS unsigned char* lds, int item, const bf16_t* QS, const float* LF, const bf16_t* KK, const bf16_t* VV, bf16_t* YAB) {
;     ...
;         for (int i = 0; i < 16; ++i) {
;             const float bb = pre + bl[i];
;             const float e1 = __expf(fminf(fmaxf(bb - mref, -80.f), 80.f)), e2 = __builtin_amdgcn_rcpf(e1);
;             const float q = bf2f(qv[i]), kx = bf2f(kv[i]);
;             const int s = part * 16 + i;
;             QT[s * 136 + k] = f2bf(q * e1); KT[s * 136 + k] = f2bf(kx * e2); QH[s * 136 + k] = f2bf(q * e1 * em); kd[i] = kx * e2 * ebm;
;         }
	s_add_u32 s98, s24, 0x1de22000
	s_addc_u32 s99, s25, 0
	global_load_ushort v168, v100, s[98:99] offset:2048
	v_add_f32_e32 v220, v220, v211
	v_mul_f32_e32 v221, v221, v224
	v_and_b32_e32 v225, 0xffff0000, v204
	v_lshlrev_b32_e32 v224, 16, v204
	s_add_u32 s98, s24, 0x21e22000
	s_addc_u32 s99, s25, 0
	global_load_ushort v204, v100, s[98:99]
	global_load_ushort v234, v100, s[98:99] offset:2048
	v_sub_f32_e32 v220, v220, v21
	v_pk_mul_f32 v[222:223], v[222:223], v[224:225]
	v_med3_f32 v220, v220, s2, v165
	v_cvt_pk_bf16_f32 v224, v222, s0
	v_mul_f32_e32 v220, 0x3fb8aa3b, v220
	v_add_f32_e32 v219, v219, v211
	ds_write_b16 v226, v224 offset:18224
	v_pk_mul_f32 v[224:225], v[20:21], v[222:223] op_sel_hi:[0,1]
	v_exp_f32_e32 v222, v220
	v_sub_f32_e32 v219, v219, v21
	v_cvt_pk_bf16_f32 v227, v221, s0
	v_mul_f32_e32 v221, v213, v221
	v_med3_f32 v219, v219, s2, v165
	v_cvt_pk_bf16_f32 v221, v221, s0
	v_cvt_pk_bf16_f32 v220, v223, s0
	v_mul_f32_e32 v219, 0x3fb8aa3b, v219
	ds_write_b16 v226, v227 offset:1088
	ds_write_b16 v226, v220 offset:18496
	ds_write_b16 v226, v221 offset:35904
	v_lshlrev_b32_e32 v221, 16, v170
	s_add_u32 s98, s24, 0x1de23000
	s_addc_u32 s99, s25, 0
	global_load_ushort v170, v100, s[98:99]
	v_exp_f32_e32 v219, v219
	v_mul_f32_e32 v221, v222, v221
	v_rcp_f32_e32 v220, v222
	v_cvt_pk_bf16_f32 v222, v221, s0
	v_mul_f32_e32 v221, v213, v221
	v_cvt_pk_bf16_f32 v221, v221, s0
	ds_write_b16 v226, v221 offset:36176
	v_rcp_f32_e32 v221, v219
	ds_write_b16 v226, v222 offset:1360
	v_lshlrev_b32_e32 v222, 16, v174
	s_add_u32 s98, s24, 0x1de23000
	s_addc_u32 s99, s25, 0
	global_load_ushort v174, v100, s[98:99] offset:2048
	v_add_f32_e32 v218, v218, v211
	v_mul_f32_e32 v219, v219, v222
	v_and_b32_e32 v223, 0xffff0000, v205
	v_lshlrev_b32_e32 v222, 16, v205
	s_add_u32 s98, s24, 0x21e23000
	s_addc_u32 s99, s25, 0
	global_load_ushort v205, v100, s[98:99]
	global_load_ushort v235, v100, s[98:99] offset:2048
	v_sub_f32_e32 v218, v218, v21
	v_pk_mul_f32 v[220:221], v[220:221], v[222:223]
	v_med3_f32 v218, v218, s2, v165
	v_cvt_pk_bf16_f32 v222, v220, s0
	v_mul_f32_e32 v218, 0x3fb8aa3b, v218
	v_add_f32_e32 v217, v217, v211
	ds_write_b16 v226, v222 offset:18768
	v_pk_mul_f32 v[222:223], v[20:21], v[220:221] op_sel_hi:[0,1]
	v_exp_f32_e32 v220, v218
	v_sub_f32_e32 v217, v217, v21
	v_cvt_pk_bf16_f32 v227, v219, s0
	v_mul_f32_e32 v219, v213, v219
	v_med3_f32 v217, v217, s2, v165
	v_cvt_pk_bf16_f32 v219, v219, s0
	v_cvt_pk_bf16_f32 v218, v221, s0
	v_mul_f32_e32 v217, 0x3fb8aa3b, v217
	ds_write_b16 v226, v227 offset:1632
	ds_write_b16 v226, v218 offset:19040
	ds_write_b16 v226, v219 offset:36448
	v_lshlrev_b32_e32 v219, 16, v189
	s_add_u32 s98, s24, 0x1de24000
	s_addc_u32 s99, s25, 0
	global_load_ushort v189, v100, s[98:99]
	v_exp_f32_e32 v217, v217
	v_mul_f32_e32 v219, v220, v219
	v_rcp_f32_e32 v218, v220
	v_cvt_pk_bf16_f32 v220, v219, s0
	v_mul_f32_e32 v219, v213, v219
	v_cvt_pk_bf16_f32 v219, v219, s0
	ds_write_b16 v226, v219 offset:36720
	v_rcp_f32_e32 v219, v217
	ds_write_b16 v226, v220 offset:1904
	v_lshlrev_b32_e32 v220, 16, v191
	s_add_u32 s98, s24, 0x1de24000
	s_addc_u32 s99, s25, 0
	global_load_ushort v191, v100, s[98:99] offset:2048
	v_add_f32_e32 v216, v216, v211
	v_mul_f32_e32 v217, v217, v220
	v_and_b32_e32 v221, 0xffff0000, v206
	v_lshlrev_b32_e32 v220, 16, v206
	s_add_u32 s98, s24, 0x21e24000
	s_addc_u32 s99, s25, 0
	global_load_ushort v206, v100, s[98:99]
	global_load_ushort v236, v100, s[98:99] offset:2048
	v_sub_f32_e32 v216, v216, v21
	v_pk_mul_f32 v[218:219], v[218:219], v[220:221]
	v_med3_f32 v216, v216, s2, v165
	v_cvt_pk_bf16_f32 v220, v218, s0
	v_mul_f32_e32 v216, 0x3fb8aa3b, v216
	v_add_f32_e32 v215, v215, v211
	ds_write_b16 v226, v220 offset:19312
	v_pk_mul_f32 v[220:221], v[20:21], v[218:219] op_sel_hi:[0,1]
	v_exp_f32_e32 v218, v216
	v_sub_f32_e32 v215, v215, v21
	v_cvt_pk_bf16_f32 v227, v217, s0
	v_mul_f32_e32 v217, v213, v217
	v_med3_f32 v215, v215, s2, v165
	v_cvt_pk_bf16_f32 v217, v217, s0
	v_cvt_pk_bf16_f32 v216, v219, s0
	v_mul_f32_e32 v215, 0x3fb8aa3b, v215
	ds_write_b16 v226, v227 offset:2176
	ds_write_b16 v226, v216 offset:19584
	ds_write_b16 v226, v217 offset:36992
	v_lshlrev_b32_e32 v217, 16, v193
	s_add_u32 s98, s24, 0x1de25000
	s_addc_u32 s99, s25, 0
	global_load_ushort v193, v100, s[98:99]
	v_exp_f32_e32 v215, v215
	v_mul_f32_e32 v217, v218, v217
	v_rcp_f32_e32 v216, v218
	v_cvt_pk_bf16_f32 v218, v217, s0
	v_mul_f32_e32 v217, v213, v217
	v_cvt_pk_bf16_f32 v217, v217, s0
	ds_write_b16 v226, v217 offset:37264
	v_rcp_f32_e32 v217, v215
	ds_write_b16 v226, v218 offset:2448
	v_lshlrev_b32_e32 v218, 16, v196
	s_add_u32 s98, s24, 0x1de25000
	s_addc_u32 s99, s25, 0
	global_load_ushort v196, v100, s[98:99] offset:2048
	v_add_f32_e32 v214, v214, v211
	v_mul_f32_e32 v215, v215, v218
	v_and_b32_e32 v219, 0xffff0000, v207
	v_lshlrev_b32_e32 v218, 16, v207
	s_add_u32 s98, s24, 0x21e25000
; #define LAS __attribute__((address_space(3)))
; __device__ __forceinline__ unsigned cvt_pk_bf16(float lo, float hi) { f32x2_c v = {lo, hi}; bf16x2_c r = __builtin_convertvector(v, bf16x2_c); return __builtin_bit_cast(unsigned, r); }
; __device__ __forceinline__ bf16_t f2bf(float f) { return (bf16_t)(cvt_pk_bf16(f, 0.f) & 0xffffu); }
; __device__ __forceinline__ float bf2f(bf16_t b) { return __uint_as_float(((unsigned)b) << 16); }
; #define HG_LOAD(c) do { const size_t r_ = row0 + (size_t)(c) * 64; \
;         _Pragma("unroll") for (int i = 0; i < 16; ++i) { const size_t p_ = (r_ + part * 16 + i) * HW + colq; lfv[i] = LF[p_]; qv[i] = QS[p_]; kv[i] = KK[p_]; } \
;         _Pragma("unroll") for (int i = 0; i < 8; ++i) vr[i] = VV[(r_ + sg * 8 + i) * HW + colv]; } while (0)
; __device__ __forceinline__ void hgrn_item(LAS unsigned char* lds, int item, const bf16_t* QS, const float* LF, const bf16_t* KK, const bf16_t* VV, bf16_t* YAB) {
;     ...
;         for (int i = 0; i < 16; ++i) {
;             const float bb = pre + bl[i];
;             const float e1 = __expf(fminf(fmaxf(bb - mref, -80.f), 80.f)), e2 = __builtin_amdgcn_rcpf(e1);
;             const float q = bf2f(qv[i]), kx = bf2f(kv[i]);
;             const int s = part * 16 + i;
;             QT[s * 136 + k] = f2bf(q * e1); KT[s * 136 + k] = f2bf(kx * e2); QH[s * 136 + k] = f2bf(q * e1 * em); kd[i] = kx * e2 * ebm;
;         }
;         { u32x4 w0, w1;
;           w0.x = cvt_pk_bf16(kd[0], kd[1]); w0.y = cvt_pk_bf16(kd[2], kd[3]); w0.z = cvt_pk_bf16(kd[4], kd[5]); w0.w = cvt_pk_bf16(kd[6], kd[7]);
;           w1.x = cvt_pk_bf16(kd[8], kd[9]); w1.y = cvt_pk_bf16(kd[10], kd[11]); w1.z = cvt_pk_bf16(kd[12], kd[13]); w1.w = cvt_pk_bf16(kd[14], kd[15]);
;           *(LAS u32x4*)(KD + k * 72 + part * 16) = w0; *(LAS u32x4*)(KD + k * 72 + part * 16 + 8) = w1; }
;         if (part == 0) DD[k] = em * ebm;
;         { u32x4 w; w.x = (unsigned)vr[0] | ((unsigned)vr[1] << 16); w.y = (unsigned)vr[2] | ((unsigned)vr[3] << 16); w.z = (unsigned)vr[4] | ((unsigned)vr[5] << 16); w.w = (unsigned)vr[6] | ((unsigned)vr[7] << 16);
;           *(LAS u32x4*)(VT + vv * 72 + sg * 8) = w; }
;         __syncthreads();
;         if (c + 1 < 64) HG_LOAD(c + 1);
	s_addc_u32 s99, s25, 0
	global_load_ushort v207, v100, s[98:99]
	global_load_ushort v237, v100, s[98:99] offset:2048
	v_sub_f32_e32 v214, v214, v21
	v_pk_mul_f32 v[216:217], v[216:217], v[218:219]
	v_med3_f32 v214, v214, s2, v165
	v_cvt_pk_bf16_f32 v218, v216, s0
	v_mul_f32_e32 v214, 0x3fb8aa3b, v214
	v_add_f32_e32 v212, v212, v211
	ds_write_b16 v226, v218 offset:19856
	v_pk_mul_f32 v[218:219], v[20:21], v[216:217] op_sel_hi:[0,1]
	v_exp_f32_e32 v216, v214
	v_sub_f32_e32 v212, v212, v21
	v_cvt_pk_bf16_f32 v227, v215, s0
	v_mul_f32_e32 v215, v213, v215
	v_med3_f32 v212, v212, s2, v165
	v_cvt_pk_bf16_f32 v215, v215, s0
	v_cvt_pk_bf16_f32 v214, v217, s0
	v_mul_f32_e32 v212, 0x3fb8aa3b, v212
	ds_write_b16 v226, v227 offset:2720
	ds_write_b16 v226, v214 offset:20128
	ds_write_b16 v226, v215 offset:37536
	v_lshlrev_b32_e32 v215, 16, v200
	s_add_u32 s98, s24, 0x1de26000
	s_addc_u32 s99, s25, 0
	global_load_ushort v200, v100, s[98:99]
	v_exp_f32_e32 v212, v212
	v_mul_f32_e32 v215, v216, v215
	v_rcp_f32_e32 v214, v216
	v_cvt_pk_bf16_f32 v216, v215, s0
	v_mul_f32_e32 v215, v213, v215
	v_cvt_pk_bf16_f32 v215, v215, s0
	ds_write_b16 v226, v215 offset:37808
	v_rcp_f32_e32 v215, v212
	ds_write_b16 v226, v216 offset:2992
	v_lshlrev_b32_e32 v216, 16, v194
	s_add_u32 s98, s24, 0x1de26000
	s_addc_u32 s99, s25, 0
	global_load_ushort v194, v100, s[98:99] offset:2048
	v_mul_f32_e32 v212, v212, v216
	v_and_b32_e32 v217, 0xffff0000, v208
	v_lshlrev_b32_e32 v216, 16, v208
	v_pk_mul_f32 v[214:215], v[214:215], v[216:217]
	s_add_u32 s98, s24, 0x21e26000
	s_addc_u32 s99, s25, 0
	global_load_ushort v208, v100, s[98:99]
	global_load_ushort v238, v100, s[98:99] offset:2048
	v_add_f32_e32 v210, v210, v211
	v_cvt_pk_bf16_f32 v216, v214, s0
	v_sub_f32_e32 v210, v210, v21
	v_add_f32_e32 v26, v26, v211
	ds_write_b16 v226, v216 offset:20400
	v_pk_mul_f32 v[216:217], v[20:21], v[214:215] op_sel_hi:[0,1]
	v_med3_f32 v210, v210, s2, v165
	v_sub_f32_e32 v21, v26, v21
	v_mul_f32_e32 v210, 0x3fb8aa3b, v210
	v_med3_f32 v21, v21, s2, v165
	v_exp_f32_e32 v214, v210
	v_mul_f32_e32 v21, 0x3fb8aa3b, v21
	v_cvt_pk_bf16_f32 v227, v212, s0
	v_mul_f32_e32 v212, v213, v212
	v_exp_f32_e32 v21, v21
	v_cvt_pk_bf16_f32 v212, v212, s0
	v_cvt_pk_bf16_f32 v210, v215, s0
	ds_write_b16 v226, v227 offset:3264
	ds_write_b16 v226, v210 offset:20672
	ds_write_b16 v226, v212 offset:38080
	v_lshlrev_b32_e32 v212, 16, v199
	s_add_u32 s98, s24, 0x1de27000
	s_addc_u32 s99, s25, 0
	global_load_ushort v199, v100, s[98:99]
	v_mul_f32_e32 v212, v214, v212
	v_rcp_f32_e32 v210, v214
	v_mul_f32_e32 v26, v213, v212
	v_rcp_f32_e32 v211, v21
	v_cvt_pk_bf16_f32 v26, v26, s0
	v_cvt_pk_bf16_f32 v214, v212, s0
	ds_write_b16 v226, v26 offset:38352
	v_lshlrev_b32_e32 v26, 16, v203
	s_add_u32 s98, s24, 0x1de27000
	s_addc_u32 s99, s25, 0
	global_load_ushort v203, v100, s[98:99] offset:2048
	ds_write_b16 v226, v214 offset:3536
	v_mul_f32_e32 v21, v21, v26
	v_and_b32_e32 v215, 0xffff0000, v209
	v_lshlrev_b32_e32 v214, 16, v209
	s_add_u32 s98, s24, 0x21e27000
	s_addc_u32 s99, s25, 0
	global_load_ushort v209, v100, s[98:99]
	global_load_ushort v239, v100, s[98:99] offset:2048
	v_cvt_pk_bf16_f32 v26, v21, s0
	v_mul_f32_e32 v21, v213, v21
	v_pk_mul_f32 v[210:211], v[210:211], v[214:215]
	v_cvt_pk_bf16_f32 v21, v21, s0
	v_cvt_pk_bf16_f32 v212, v210, s0
	ds_write_b16 v226, v212 offset:20944
	ds_write_b16 v226, v26 offset:3808
	v_cvt_pk_bf16_f32 v26, v211, s0
	v_cvt_pk_bf16_f32 v22, v22, v23
	v_cvt_pk_bf16_f32 v23, v24, v25
	v_cvt_pk_bf16_f32 v24, v224, v225
	v_cvt_pk_bf16_f32 v25, v222, v223
	v_pk_mul_f32 v[210:211], v[20:21], v[210:211] op_sel_hi:[0,1]
	ds_write_b16 v226, v26 offset:21216
	ds_write_b16 v226, v21 offset:38624
	v_cvt_pk_bf16_f32 v214, v220, v221
	v_cvt_pk_bf16_f32 v215, v218, v219
	v_cvt_pk_bf16_f32 v216, v216, v217
	v_cvt_pk_bf16_f32 v217, v210, v211
	ds_write_b128 v127, v[22:25] offset:52224
	ds_write_b128 v127, v[214:217] offset:52240
	s_and_saveexec_b64 s[38:39], s[72:73]
	v_mul_f32_e32 v20, v213, v20
	ds_write_b32 v134, v20
	s_or_b64 exec, exec, s[38:39]
	s_cmp_eq_u32 s0, 0xfc0000
	ds_write_b128 v128, v[8:11]
	s_add_u32 s98, s24, 0x25e20000
	s_addc_u32 s99, s25, 0
	global_load_ushort v8, v98, s[98:99]
	global_load_ushort v240, v98, s[98:99] offset:2048
	s_add_u32 s98, s24, 0x25e21000
	s_addc_u32 s99, s25, 0
	global_load_ushort v9, v98, s[98:99]
	global_load_ushort v241, v98, s[98:99] offset:2048
	s_add_u32 s98, s24, 0x25e22000
	s_addc_u32 s99, s25, 0
	global_load_ushort v10, v98, s[98:99]
	global_load_ushort v242, v98, s[98:99] offset:2048
	s_add_u32 s98, s24, 0x25e23000
	s_addc_u32 s99, s25, 0
	global_load_ushort v11, v98, s[98:99]
	global_load_ushort v243, v98, s[98:99] offset:2048
	s_waitcnt lgkmcnt(0)
	s_barrier
	s_cbranch_scc1 .LBB0_705
	s_mov_b64 s[90:91], s[26:27]
	s_mov_b64 s[88:89], s[24:25]
	s_mov_b64 s[86:87], s[22:23]
	s_mov_b64 s[84:85], s[20:21]
